# features: LoRA weight-fragment loads batched (2 round trips instead of ~20), tile zrw rows prefetched into L2 at tile start
# speedup vs baseline: 1.0085x; 1.0085x over previous
; #define UFOR(v, n) _Pragma("unroll") for (int v = 0; v < (n); ++v)
; #define LDS_BARRIER() do { asm volatile("s_waitcnt lgkmcnt(0)" ::: "memory"); __builtin_amdgcn_s_barrier(); asm volatile("" ::: "memory"); } while (0)
; __device__ __forceinline__ void phase_features(KP p, int l) {
;     ...
;   for (int it = bid_; it < MT / 16; it += gridDim.x) {
;     const int R0 = it * 16;
;     int s0, len, mr; seqinfo(R0, s0, len, mr);
;     LDS_BARRIER();
;     if (tid_ < 192) sbl[tid_] = 0.f;
; #pragma unroll 9
;     for (int i = 0; i < 9; ++i) {
;       const int q = tid_ + 512 * i, tok = q / 288, grp = q % 288, sec = grp / 96, r = R0 + tok, col = grp * 8, ch = col - sec * RW;
;       const bool hm = r - 1 >= s0, hp = r + 1 < s0 + len;
;       const u16* z = zrw + (size_t)r * RWC + col;
;       float c[8], a[8], b[8], o[8], m[8];
;       unpack8(*(const uint4*)z, c);
;       if (hm) unpack8(*(const uint4*)(z - RWC), a); else UFOR(x, 8) a[x] = 0.f;
;       if (hp) unpack8(*(const uint4*)(z + RWC), b); else UFOR(x, 8) b[x] = 0.f;
.LBB0_523:
	s_waitcnt lgkmcnt(0)
	s_barrier
	s_mov_b64 s[52:53], exec
	v_readlane_b32 s6, v255, 15
	v_readlane_b32 s7, v255, 16
	s_and_b64 s[6:7], s[52:53], s[6:7]
	s_mov_b64 exec, s[6:7]
	ds_write_b32 v157, v133
	s_or_b64 exec, exec, s[52:53]
	s_lshl_b32 s6, s14, 4
	s_add_i32 s6, s6, -1
	s_mulk_i32 s6, 0x1400
	s_ashr_i32 s7, s6, 31
	s_add_u32 s6, s6, s78
	s_addc_u32 s7, s7, s79
	v_lshlrev_b32_e32 v244, 7, v135
	v_readfirstlane_b32 s52, v135
	global_load_dword v246, v244, s[6:7]
	v_add_u32_e32 v245, 0x10000, v244
	s_cmpk_lt_u32 s52, 0x100
	s_cbranch_scc0 .Lfeat_pf_done
	global_load_dword v247, v245, s[6:7]
.Lfeat_pf_done:
	s_lshl_b32 s15, s14, 4
	v_add_u32_e32 v24, s15, v166
	s_movk_i32 s1, 0x1400
	v_mad_i64_i32 v[4:5], s[6:7], v24, s1, v[46:47]
	global_load_dwordx4 v[0:3], v[4:5], off
	s_cmpk_lt_i32 s14, 0x800
	s_cselect_b64 s[52:53], -1, 0
	s_and_b64 s[6:7], s[52:53], exec
	s_mov_b32 s1, 0x7fffff00
	s_cselect_b32 s6, 0xffffc000, s1
	s_and_b32 s38, s6, s15
	v_cmp_lt_i32_e32 vcc, s38, v24
	v_mov_b32_e32 v8, 0
	v_mov_b32_e32 v12, 0
	v_mov_b32_e32 v13, 0
	v_mov_b32_e32 v6, 0
	v_mov_b32_e32 v7, 0
	v_mov_b32_e32 v16, 0
	v_mov_b32_e32 v17, 0
	v_mov_b32_e32 v14, 0
	v_mov_b32_e32 v15, 0
	s_and_saveexec_b64 s[56:57], vcc
	s_cbranch_execz .LBB0_527
	v_add_co_u32_e32 v6, vcc, 0xfffff000, v4
	s_nop 1
	v_addc_co_u32_e32 v7, vcc, -1, v5, vcc
	global_load_dwordx4 v[16:19], v[6:7], off offset:-1024
	s_waitcnt vmcnt(0)
	v_lshlrev_b32_e32 v12, 16, v16
	v_and_b32_e32 v13, 0xffff0000, v16
	v_lshlrev_b32_e32 v6, 16, v17
	v_and_b32_e32 v7, 0xffff0000, v17
	v_lshlrev_b32_e32 v16, 16, v18
	v_and_b32_e32 v17, 0xffff0000, v18
	v_lshlrev_b32_e32 v14, 16, v19
	v_and_b32_e32 v15, 0xffff0000, v19

; #define UFOR(v, n) _Pragma("unroll") for (int v = 0; v < (n); ++v)
; #define MFMA16(a, b, c) __builtin_amdgcn_mfma_f32_16x16x32_bf16(a, b, c, 0, 0, 0)
; __device__ __forceinline__ void phase_features(KP p, int l) {
;     ...
;     for (int u = w * 3; u < w * 3 + 3; ++u) {
;       const int hd = u >> 1, chb = hd * 64 + (u & 1) * 32;
;       f32x4 aw0[2], aw1[2], aa0[2], aa1[2], ag[2];
;       UFOR(n, 2) { aw0[n] = (f32x4){0.f, 0.f, 0.f, 0.f}; aw1[n] = aw0[n]; aa0[n] = aw0[n]; aa1[n] = aw0[n]; ag[n] = aw0[n]; }
;       UFOR(ks, 2) {
;         const bf16x8 atw = *(const bf16x8*)(smem + F_AIN + fr * 528 + (ks * 32 + fq * 8) * 2);
;         const bf16x8 aad = *(const bf16x8*)(smem + F_AIN + fr * 528 + (64 + ks * 32 + fq * 8) * 2);
;         UFOR(n, 2) {
;           const int ch = chb + n * 16 + fr;
;           aw0[n] = MFMA16(atw, *(const bf16x8*)(wupT + (size_t)ch * 64 + ks * 32 + fq * 8), aw0[n]);
;           aw1[n] = MFMA16(atw, *(const bf16x8*)(wupT + (size_t)(RW + ch) * 64 + ks * 32 + fq * 8), aw1[n]);
;           aa0[n] = MFMA16(aad, *(const bf16x8*)(aupT + (size_t)ch * 64 + ks * 32 + fq * 8), aa0[n]);
;           aa1[n] = MFMA16(aad, *(const bf16x8*)(aupT + (size_t)(RW + ch) * 64 + ks * 32 + fq * 8), aa1[n]);
;         }
;       }
;       UFOR(ks, 4) {
;         const bf16x8 asg = *(const bf16x8*)(smem + F_AIN + fr * 528 + (128 + ks * 32 + fq * 8) * 2);
;         UFOR(n, 2) {
;           const int ch = chb + n * 16 + fr;
;           ag[n] = MFMA16(asg, *(const bf16x8*)(gupT + (size_t)ch * 128 + ks * 32 + fq * 8), ag[n]);
;         }
;       }
;       UFOR(n, 2) UFOR(j, 4) {
;         const int e = (fq * 4 + j) * 32 + n * 16 + fr;
;         ((float*)stg)[e] = aw0[n][j]; ((float*)(stg + 2048))[e] = aw1[n][j];
;         ((u16*)(stg + 4096))[e] = f2bf(aa0[n][j]); ((u16*)(stg + 5120))[e] = f2bf(aa1[n][j]); ((u16*)(stg + 6144))[e] = f2bf(ag[n][j]);
;       }
.LBB0_687:
	v_add_u32_e32 v0, s18, v159
	v_ashrrev_i32_e32 v191, 1, v0
	v_and_b32_e32 v0, 32, v190
	v_lshl_or_b32 v120, v191, 6, v0
	v_or_b32_e32 v130, v120, v156
	v_ashrrev_i32_e32 v131, 31, v130
	v_lshlrev_b64 v[154:155], 7, v[130:131]
	v_lshl_add_u64 v[136:137], v[38:39], 0, v[154:155]
	v_lshl_add_u64 v[192:193], v[40:41], 0, v[154:155]
	s_mov_b64 s[6:7], 0x18000
	ds_read_b128 v[140:143], v187
	ds_read_b128 v[144:147], v187 offset:128
	v_lshl_add_u64 v[138:139], v[136:137], 0, s[6:7]
	v_lshl_add_u64 v[194:195], v[192:193], 0, s[6:7]
	ds_read_b128 v[148:151], v187 offset:64
	ds_read_b128 v[122:125], v187 offset:192
	global_load_dwordx4 v[0:3], v[136:137], off
	global_load_dwordx4 v[4:7], v[136:137], off offset:2048
	global_load_dwordx4 v[8:11], v[138:139], off
	global_load_dwordx4 v[12:15], v[138:139], off offset:2048
	global_load_dwordx4 v[16:19], v[192:193], off
	global_load_dwordx4 v[20:23], v[192:193], off offset:2048
	global_load_dwordx4 v[24:27], v[194:195], off
	global_load_dwordx4 v[28:31], v[194:195], off offset:2048
	global_load_dwordx4 v[212:215], v[136:137], off offset:64
	global_load_dwordx4 v[216:219], v[136:137], off offset:2112
	global_load_dwordx4 v[220:223], v[138:139], off offset:64
	global_load_dwordx4 v[224:227], v[138:139], off offset:2112
	global_load_dwordx4 v[228:231], v[192:193], off offset:64
	global_load_dwordx4 v[232:235], v[192:193], off offset:2112
	global_load_dwordx4 v[236:239], v[194:195], off offset:64
	global_load_dwordx4 v[240:243], v[194:195], off offset:2112
	v_lshlrev_b64 v[154:155], 8, v[130:131]
	v_lshl_add_u64 v[196:197], v[42:43], 0, v[154:155]
	s_mov_b64 s[6:7], 0x1000
	s_nop 0
	v_lshl_add_u64 v[152:153], v[196:197], 0, s[6:7]
	s_mov_b64 s[6:7], 0x18800
	s_waitcnt vmcnt(8) lgkmcnt(0)
	v_mfma_f32_16x16x32_bf16 v[0:3], v[140:143], v[0:3], 0
	v_mfma_f32_16x16x32_bf16 v[4:7], v[140:143], v[4:7], 0
	v_mfma_f32_16x16x32_bf16 v[8:11], v[140:143], v[8:11], 0
	v_mfma_f32_16x16x32_bf16 v[12:15], v[140:143], v[12:15], 0
	v_mfma_f32_16x16x32_bf16 v[16:19], v[144:147], v[16:19], 0
	v_mfma_f32_16x16x32_bf16 v[20:23], v[144:147], v[20:23], 0
	v_mfma_f32_16x16x32_bf16 v[24:27], v[144:147], v[24:27], 0
	v_mfma_f32_16x16x32_bf16 v[28:31], v[144:147], v[28:31], 0
	s_waitcnt vmcnt(0)
	v_mfma_f32_16x16x32_bf16 v[0:3], v[148:151], v[212:215], v[0:3]
	v_mfma_f32_16x16x32_bf16 v[4:7], v[148:151], v[216:219], v[4:7]
	v_mfma_f32_16x16x32_bf16 v[8:11], v[148:151], v[220:223], v[8:11]
	v_mfma_f32_16x16x32_bf16 v[12:15], v[148:151], v[224:227], v[12:15]
	v_mfma_f32_16x16x32_bf16 v[16:19], v[122:125], v[228:231], v[16:19]
	v_mfma_f32_16x16x32_bf16 v[20:23], v[122:125], v[232:235], v[20:23]
	v_mfma_f32_16x16x32_bf16 v[24:27], v[122:125], v[236:239], v[24:27]
	v_mfma_f32_16x16x32_bf16 v[28:31], v[122:125], v[240:243], v[28:31]
	global_load_dwordx4 v[212:215], v[196:197], off
	global_load_dwordx4 v[216:219], v[196:197], off offset:64
	global_load_dwordx4 v[220:223], v[196:197], off offset:128
	global_load_dwordx4 v[224:227], v[196:197], off offset:192
	global_load_dwordx4 v[228:231], v[152:153], off
	global_load_dwordx4 v[232:235], v[152:153], off offset:64
	global_load_dwordx4 v[236:239], v[152:153], off offset:128
	global_load_dwordx4 v[240:243], v[152:153], off offset:192
	ds_read_b128 v[140:143], v187 offset:256
	ds_read_b128 v[144:147], v187 offset:320
	ds_read_b128 v[148:151], v187 offset:384
	ds_read_b128 v[122:125], v187 offset:448
	ds_write_b32 v184, v0 offset:0
	ds_write_b32 v184, v1 offset:128
	ds_write_b32 v184, v2 offset:256
	ds_write_b32 v184, v3 offset:384
	ds_write_b32 v184, v4 offset:64
	ds_write_b32 v184, v5 offset:192
	ds_write_b32 v184, v6 offset:320
	ds_write_b32 v184, v7 offset:448
	ds_write_b32 v184, v8 offset:2048
	ds_write_b32 v184, v9 offset:2176
	ds_write_b32 v184, v10 offset:2304
	ds_write_b32 v184, v11 offset:2432
	ds_write_b32 v184, v12 offset:2112
	ds_write_b32 v184, v13 offset:2240
	ds_write_b32 v184, v14 offset:2368
	ds_write_b32 v184, v15 offset:2496
	v_bfe_u32 v32, v16, 16, 1
	v_add3_u32 v32, v16, v32, s31
	ds_write_b16_d16_hi v189, v32 offset:4096
	v_bfe_u32 v33, v17, 16, 1
	v_add3_u32 v33, v17, v33, s31
	ds_write_b16_d16_hi v189, v33 offset:4160
	v_bfe_u32 v32, v18, 16, 1
	v_add3_u32 v32, v18, v32, s31
	ds_write_b16_d16_hi v189, v32 offset:4224
	v_bfe_u32 v33, v19, 16, 1
	v_add3_u32 v33, v19, v33, s31
	ds_write_b16_d16_hi v189, v33 offset:4288
	v_bfe_u32 v32, v20, 16, 1
	v_add3_u32 v32, v20, v32, s31
	ds_write_b16_d16_hi v189, v32 offset:4128
	v_bfe_u32 v33, v21, 16, 1
	v_add3_u32 v33, v21, v33, s31
	ds_write_b16_d16_hi v189, v33 offset:4192
	v_bfe_u32 v32, v22, 16, 1
	v_add3_u32 v32, v22, v32, s31
	ds_write_b16_d16_hi v189, v32 offset:4256
	v_bfe_u32 v33, v23, 16, 1
	v_add3_u32 v33, v23, v33, s31
	ds_write_b16_d16_hi v189, v33 offset:4320
	v_bfe_u32 v32, v24, 16, 1
	v_add3_u32 v32, v24, v32, s31
	ds_write_b16_d16_hi v189, v32 offset:5120
	v_bfe_u32 v33, v25, 16, 1
	v_add3_u32 v33, v25, v33, s31
	ds_write_b16_d16_hi v189, v33 offset:5184
	v_bfe_u32 v32, v26, 16, 1
	v_add3_u32 v32, v26, v32, s31
	ds_write_b16_d16_hi v189, v32 offset:5248
	v_bfe_u32 v33, v27, 16, 1
	v_add3_u32 v33, v27, v33, s31
	ds_write_b16_d16_hi v189, v33 offset:5312
	v_bfe_u32 v32, v28, 16, 1
	v_add3_u32 v32, v28, v32, s31
	ds_write_b16_d16_hi v189, v32 offset:5152
	v_bfe_u32 v33, v29, 16, 1
	v_add3_u32 v33, v29, v33, s31
	ds_write_b16_d16_hi v189, v33 offset:5216
	v_bfe_u32 v32, v30, 16, 1
	v_add3_u32 v32, v30, v32, s31
	ds_write_b16_d16_hi v189, v32 offset:5280
	v_bfe_u32 v33, v31, 16, 1
	v_add3_u32 v33, v31, v33, s31
	ds_write_b16_d16_hi v189, v33 offset:5344
	s_waitcnt vmcnt(0) lgkmcnt(0)
; #define UFOR(v, n) _Pragma("unroll") for (int v = 0; v < (n); ++v)
; __device__ __forceinline__ float sigmoidf_(float x) { return 1.f / (1.f + __expf(-x)); }
; #define MFMA16(a, b, c) __builtin_amdgcn_mfma_f32_16x16x32_bf16(a, b, c, 0, 0, 0)
; __device__ __forceinline__ void phase_features(KP p, int l) {
;     ...
;       UFOR(ks, 4) {
;         const bf16x8 asg = *(const bf16x8*)(smem + F_AIN + fr * 528 + (128 + ks * 32 + fq * 8) * 2);
;         UFOR(n, 2) {
;           const int ch = chb + n * 16 + fr;
;           ag[n] = MFMA16(asg, *(const bf16x8*)(gupT + (size_t)ch * 128 + ks * 32 + fq * 8), ag[n]);
;         }
;       }
;       UFOR(n, 2) UFOR(j, 4) {
;         const int e = (fq * 4 + j) * 32 + n * 16 + fr;
;         ((float*)stg)[e] = aw0[n][j]; ((float*)(stg + 2048))[e] = aw1[n][j];
;         ((u16*)(stg + 4096))[e] = f2bf(aa0[n][j]); ((u16*)(stg + 5120))[e] = f2bf(aa1[n][j]); ((u16*)(stg + 6144))[e] = f2bf(ag[n][j]);
;       }
;       asm volatile("s_waitcnt lgkmcnt(0)" ::: "memory");
;       {
;         const int tok = lane >> 2, g4 = lane & 3, ch = chb + g4 * 8, r = R0 + tok;
;         float xw0[8], xw1[8], ya0[8], ya1[8], gg[8], kv[8], kkn[8], rr[8], cw0[8], cw1[8], ca0[8], ca1[8], cka[8], crk[8];
;         ld8f((const float*)stg + tok * 32 + g4 * 8, xw0); ld8f((const float*)(stg + 2048) + tok * 32 + g4 * 8, xw1);
;         unpack8(*(const uint4*)(stg + 4096 + (tok * 32 + g4 * 8) * 2), ya0); unpack8(*(const uint4*)(stg + 5120 + (tok * 32 + g4 * 8) * 2), ya1);
;         unpack8(*(const uint4*)(stg + 6144 + (tok * 32 + g4 * 8) * 2), gg);
;         unpack8(*(const uint4*)(smem + F_KL + (tok * RW + ch) * 2), kv); unpack8(*(const uint4*)(smem + F_KK + (tok * RW + ch) * 2), kkn);
;         unpack8(*(const uint4*)(smem + F_RL + (tok * RW + ch) * 2), rr);
;         ld8f(w0 + ch, cw0); ld8f(w0 + RW + ch, cw1); ld8f(a0 + ch, ca0); ld8f(a0 + RW + ch, ca1); ld8f(ka_ + ch, cka); ld8f(rk_ + ch, crk);
;         float d0[8], d1[8], k0[8], k1[8], b0[8], b1[8];
;         float bon = 0.f;
;         UFOR(x, 8) {
;           d0[x] = 0.6065306597126334f * sigmoidf_(cw0[x] + xw0[x]);
;           d1[x] = 0.6065306597126334f * sigmoidf_(cw1[x] + xw1[x]);
;           const float av0 = sigmoidf_(ca0[x] + ya0[x]), av1 = sigmoidf_(ca1[x] + ya1[x]);
	v_mfma_f32_16x16x32_bf16 v[212:215], v[140:143], v[212:215], 0
	v_mfma_f32_16x16x32_bf16 v[228:231], v[140:143], v[228:231], 0
	v_mfma_f32_16x16x32_bf16 v[212:215], v[144:147], v[216:219], v[212:215]
	v_mfma_f32_16x16x32_bf16 v[228:231], v[144:147], v[232:235], v[228:231]
	v_mfma_f32_16x16x32_bf16 v[212:215], v[148:151], v[220:223], v[212:215]
	v_mfma_f32_16x16x32_bf16 v[228:231], v[148:151], v[236:239], v[228:231]
	v_mfma_f32_16x16x32_bf16 v[212:215], v[122:125], v[224:227], v[212:215]
	v_mfma_f32_16x16x32_bf16 v[228:231], v[122:125], v[240:243], v[228:231]
	s_nop 7
	s_nop 1
	v_bfe_u32 v32, v212, 16, 1
	v_add3_u32 v32, v212, v32, s31
	ds_write_b16_d16_hi v189, v32 offset:6144
	v_bfe_u32 v33, v213, 16, 1
	v_add3_u32 v33, v213, v33, s31
	ds_write_b16_d16_hi v189, v33 offset:6208
	v_bfe_u32 v32, v214, 16, 1
	v_add3_u32 v32, v214, v32, s31
	ds_write_b16_d16_hi v189, v32 offset:6272
	v_bfe_u32 v33, v215, 16, 1
	v_add3_u32 v33, v215, v33, s31
	ds_write_b16_d16_hi v189, v33 offset:6336
	v_bfe_u32 v32, v228, 16, 1
	v_add3_u32 v32, v228, v32, s31
	ds_write_b16_d16_hi v189, v32 offset:6176
	v_bfe_u32 v33, v229, 16, 1
	v_add3_u32 v33, v229, v33, s31
	ds_write_b16_d16_hi v189, v33 offset:6240
	v_bfe_u32 v32, v230, 16, 1
	v_add3_u32 v32, v230, v32, s31
	ds_write_b16_d16_hi v189, v32 offset:6304
	v_bfe_u32 v33, v231, 16, 1
	v_add3_u32 v33, v231, v33, s31
	ds_write_b16_d16_hi v189, v33 offset:6368
	s_waitcnt lgkmcnt(0)
	ds_read_b128 v[18:21], v162
	ds_read_b128 v[12:15], v162 offset:16
	ds_read_b128 v[26:29], v162 offset:2048
	ds_read_b128 v[8:11], v162 offset:2064
	ds_read_b128 v[0:3], v188 offset:4096
	v_or_b32_e32 v16, v120, v161
	v_ashrrev_i32_e32 v17, 31, v16
	s_waitcnt lgkmcnt(0)
	v_lshlrev_b32_e32 v23, 16, v0
	v_and_b32_e32 v34, 0xffff0000, v0
	v_lshlrev_b32_e32 v35, 16, v1
	v_and_b32_e32 v128, 0xffff0000, v1
	v_lshlrev_b32_e32 v129, 16, v2
	v_and_b32_e32 v134, 0xffff0000, v2
	v_lshlrev_b32_e32 v139, 16, v3
	v_and_b32_e32 v196, 0xffff0000, v3
	ds_read_b128 v[0:3], v188 offset:5120
	s_waitcnt lgkmcnt(0)
	v_lshlrev_b32_e32 v130, 16, v0
	v_and_b32_e32 v131, 0xffff0000, v0
	v_add_u32_e32 v0, v16, v163
	v_lshl_add_u32 v192, v0, 1, 0
	v_lshlrev_b32_e32 v137, 16, v1
	v_and_b32_e32 v138, 0xffff0000, v1
	v_lshlrev_b32_e32 v140, 16, v2
	v_and_b32_e32 v141, 0xffff0000, v2
	v_lshlrev_b32_e32 v195, 16, v3
	v_and_b32_e32 v206, 0xffff0000, v3
	ds_read_b128 v[0:3], v192 offset:57600
	s_waitcnt lgkmcnt(0)
	v_lshlrev_b32_e32 v136, 16, v0
	v_and_b32_e32 v143, 0xffff0000, v0
	v_lshlrev_b32_e32 v193, 16, v1
	v_and_b32_e32 v194, 0xffff0000, v1
	v_lshlrev_b64 v[0:1], 2, v[16:17]
	v_lshlrev_b32_e32 v208, 16, v2
	v_and_b32_e32 v209, 0xffff0000, v2
	v_lshlrev_b32_e32 v210, 16, v3
	v_and_b32_e32 v211, 0xffff0000, v3
	v_lshl_add_u64 v[2:3], s[60:61], 0, v[0:1]
	global_load_dwordx4 v[124:127], v[2:3], off offset:16
	global_load_dwordx4 v[30:33], v[2:3], off
	global_load_dwordx4 v[144:147], v[2:3], off offset:3088
	global_load_dwordx4 v[120:123], v[2:3], off offset:3072
	v_lshl_add_u64 v[2:3], s[64:65], 0, v[0:1]
	global_load_dwordx4 v[148:151], v[2:3], off offset:16
	global_load_dwordx4 v[152:155], v[2:3], off
	global_load_dwordx4 v[202:205], v[2:3], off offset:3088
	global_load_dwordx4 v[198:201], v[2:3], off offset:3072
	v_mul_f32_e32 v197, 0.5, v136
	v_lshl_add_u64 v[24:25], s[68:69], 0, v[0:1]
	v_lshl_add_u64 v[4:5], s[72:73], 0, v[0:1]
	global_load_dwordx4 v[0:3], v[4:5], off offset:16
	s_nop 0
	global_load_dwordx4 v[4:7], v[4:5], off
	s_waitcnt vmcnt(9)
	v_add_f32_e32 v12, v12, v124
	s_waitcnt vmcnt(8)
	v_add_f32_e32 v19, v19, v31
	v_mul_f32_e32 v19, 0xbfb8aa3b, v19
	s_waitcnt vmcnt(6)
	v_add_f32_e32 v22, v26, v120
	v_exp_f32_e32 v26, v19
	v_add_f32_e32 v19, v27, v121
	v_mul_f32_e32 v19, 0xbfb8aa3b, v19
	s_waitcnt vmcnt(4)
	v_add_f32_e32 v23, v152, v23
	v_exp_f32_e32 v136, v19
	v_add_f32_e32 v19, v153, v34
	v_mul_f32_e32 v23, 0xbfb8aa3b, v23
	v_mul_f32_e32 v19, 0xbfb8aa3b, v19
	v_exp_f32_e32 v142, v23
	s_waitcnt vmcnt(2)
	v_add_f32_e32 v23, v198, v130
	v_exp_f32_e32 v130, v19
	v_add_f32_e32 v19, v199, v131
	v_mul_f32_e32 v19, 0xbfb8aa3b, v19
	v_exp_f32_e32 v34, v19
	v_add_f32_e32 v19, v20, v32
	v_add_f32_e32 v20, v28, v122
	v_mul_f32_e32 v23, 0xbfb8aa3b, v23
	v_mul_f32_e32 v20, 0xbfb8aa3b, v20
	v_exp_f32_e32 v120, v23
	v_exp_f32_e32 v23, v20
	v_add_f32_e32 v20, v154, v35
	v_mul_f32_e32 v20, 0xbfb8aa3b, v20
	v_mul_f32_e32 v198, 0.5, v143
	v_exp_f32_e32 v143, v20
	v_add_f32_e32 v20, v200, v137
	v_mul_f32_e32 v20, 0xbfb8aa3b, v20
	v_exp_f32_e32 v121, v20
	v_add_f32_e32 v20, v21, v33
	v_mul_f32_e32 v20, 0xbfb8aa3b, v20
	v_exp_f32_e32 v27, v20
	v_add_f32_e32 v20, v29, v123
	v_mul_f32_e32 v20, 0xbfb8aa3b, v20
	v_exp_f32_e32 v137, v20
	v_add_f32_e32 v20, v155, v128
	v_mul_f32_e32 v20, 0xbfb8aa3b, v20
	v_exp_f32_e32 v131, v20
	v_add_f32_e32 v20, v201, v138
	v_add_f32_e32 v8, v8, v144
	v_mul_f32_e32 v20, 0xbfb8aa3b, v20
	v_mul_f32_e32 v8, 0xbfb8aa3b, v8
	v_exp_f32_e32 v35, v20
	v_exp_f32_e32 v20, v8
	v_add_f32_e32 v8, v148, v129
	v_mul_f32_e32 v8, 0xbfb8aa3b, v8
	v_exp_f32_e32 v128, v8
	v_add_f32_e32 v8, v202, v140
	v_mul_f32_e32 v8, 0xbfb8aa3b, v8
	v_exp_f32_e32 v32, v8
	v_add_f32_e32 v8, v13, v125
	v_mul_f32_e32 v8, 0xbfb8aa3b, v8
	v_exp_f32_e32 v138, v8
	v_add_f32_e32 v8, v9, v145
	v_mul_f32_e32 v8, 0xbfb8aa3b, v8
	v_exp_f32_e32 v140, v8
	v_add_f32_e32 v8, v149, v134
	v_mul_f32_e32 v8, 0xbfb8aa3b, v8
	v_exp_f32_e32 v124, v8
	v_add_f32_e32 v8, v203, v141
	v_mul_f32_e32 v8, 0xbfb8aa3b, v8
	v_add_f32_e32 v18, v18, v30
	v_exp_f32_e32 v30, v8
	v_add_f32_e32 v8, v14, v126
	v_mul_f32_e32 v8, 0xbfb8aa3b, v8
	v_exp_f32_e32 v13, v8
	v_add_f32_e32 v8, v10, v146
	v_mul_f32_e32 v8, 0xbfb8aa3b, v8
; #define UFOR(v, n) _Pragma("unroll") for (int v = 0; v < (n); ++v)
; __device__ __forceinline__ float sigmoidf_(float x) { return 1.f / (1.f + __expf(-x)); }
; __device__ __forceinline__ void phase_features(KP p, int l) {
;     ...
;         UFOR(x, 8) {
;           d0[x] = 0.6065306597126334f * sigmoidf_(cw0[x] + xw0[x]);
;           d1[x] = 0.6065306597126334f * sigmoidf_(cw1[x] + xw1[x]);
;           const float av0 = sigmoidf_(ca0[x] + ya0[x]), av1 = sigmoidf_(ca1[x] + ya1[x]);
;           k0[x] = kv[x] * (1.f + (av0 - 1.f) * cka[x]); k1[x] = kv[x] * (1.f + (av1 - 1.f) * cka[x]);
;           b0[x] = kkn[x] * av0; b1[x] = kkn[x] * av1;
;           bon += rr[x] * 0.5f * (k0[x] + k1[x]) * crk[x];
;         }
;         const size_t go = (size_t)r * RW + ch;
;         *(uint4*)(FA(3) + go) = packh8(d0); *(uint4*)(FA(4) + go) = packh8(d1);
	v_exp_f32_e32 v21, v8
	v_add_f32_e32 v8, v150, v139
	v_mul_f32_e32 v8, 0xbfb8aa3b, v8
	v_exp_f32_e32 v129, v8
	v_add_f32_e32 v8, v204, v195
	v_mul_f32_e32 v8, 0xbfb8aa3b, v8
	v_exp_f32_e32 v33, v8
	v_add_f32_e32 v8, v15, v127
	v_mul_f32_e32 v8, 0xbfb8aa3b, v8
	v_exp_f32_e32 v139, v8
	v_add_f32_e32 v8, v11, v147
	v_mul_f32_e32 v8, 0xbfb8aa3b, v8
	v_mul_f32_e32 v18, 0xbfb8aa3b, v18
	v_mul_f32_e32 v19, 0xbfb8aa3b, v19
	v_exp_f32_e32 v141, v8
	v_add_f32_e32 v8, v151, v196
	v_exp_f32_e32 v18, v18
	v_exp_f32_e32 v19, v19
	v_mul_f32_e32 v8, 0xbfb8aa3b, v8
	v_exp_f32_e32 v125, v8
	v_add_f32_e32 v8, v205, v206
	v_mul_f32_e32 v8, 0xbfb8aa3b, v8
	v_exp_f32_e32 v31, v8
	v_lshl_add_u64 v[8:9], v[118:119], 0, v[16:17]
	v_lshlrev_b64 v[28:29], 1, v[8:9]
	v_pk_add_f32 v[8:9], v[18:19], 1.0 op_sel_hi:[1,0]
	v_mul_f32_e32 v12, 0xbfb8aa3b, v12
	v_div_scale_f32 v10, s[6:7], v9, v9, 1.0
	v_rcp_f32_e32 v11, v10
	v_exp_f32_e32 v12, v12
	v_mul_f32_e32 v22, 0xbfb8aa3b, v22
	v_exp_f32_e32 v22, v22
	v_fma_f32 v14, -v10, v11, 1.0
	v_fmac_f32_e32 v11, v14, v11
	v_div_scale_f32 v14, vcc, 1.0, v9, 1.0
	v_mul_f32_e32 v15, v14, v11
	v_fma_f32 v16, -v10, v15, v14
	v_fmac_f32_e32 v15, v16, v11
	v_fma_f32 v10, -v10, v15, v14
	v_div_fmas_f32 v10, v10, v11, v15
	v_div_fixup_f32 v9, v10, v9, 1.0
	v_div_scale_f32 v10, s[6:7], v8, v8, 1.0
	v_rcp_f32_e32 v11, v10
	v_pk_add_f32 v[130:131], v[130:131], 1.0 op_sel_hi:[1,0]
	v_pk_add_f32 v[124:125], v[124:125], 1.0 op_sel_hi:[1,0]
	v_lshl_add_u64 v[122:123], s[50:51], 0, v[28:29]
	v_fma_f32 v14, -v10, v11, 1.0
	v_fmac_f32_e32 v11, v14, v11
	v_div_scale_f32 v14, vcc, 1.0, v8, 1.0
	v_mul_f32_e32 v15, v14, v11
	v_fma_f32 v16, -v10, v15, v14
	v_fmac_f32_e32 v15, v16, v11
	v_fma_f32 v10, -v10, v15, v14
	v_div_fmas_f32 v10, v10, v11, v15
	v_div_fixup_f32 v8, v10, v8, 1.0
	v_pk_add_f32 v[10:11], v[26:27], 1.0 op_sel_hi:[1,0]
	v_pk_mul_f32 v[8:9], v[8:9], s[36:37] op_sel_hi:[1,0]
	v_div_scale_f32 v14, s[6:7], v11, v11, 1.0
	v_rcp_f32_e32 v15, v14
	v_cvt_pk_f16_f32 v8, v8, v9
	v_lshl_add_u64 v[126:127], s[54:55], 0, v[28:29]
	v_mul_f32_e32 v199, 0.5, v193
	v_fma_f32 v16, -v14, v15, 1.0
	v_fmac_f32_e32 v15, v16, v15
	v_div_scale_f32 v16, vcc, 1.0, v11, 1.0
	v_mul_f32_e32 v17, v16, v15
	v_fma_f32 v18, -v14, v17, v16
	v_fmac_f32_e32 v17, v18, v15
	v_fma_f32 v14, -v14, v17, v16
	v_div_fmas_f32 v14, v14, v15, v17
	v_div_fixup_f32 v11, v14, v11, 1.0
	v_div_scale_f32 v14, s[6:7], v10, v10, 1.0
	v_rcp_f32_e32 v15, v14
	v_mul_f32_e32 v200, 0.5, v194
	v_mul_f32_e32 v193, 0.5, v208
	v_mul_f32_e32 v194, 0.5, v209
	v_fma_f32 v16, -v14, v15, 1.0
	v_fmac_f32_e32 v15, v16, v15
	v_div_scale_f32 v16, vcc, 1.0, v10, 1.0
	v_mul_f32_e32 v17, v16, v15
	v_fma_f32 v18, -v14, v17, v16
	v_fmac_f32_e32 v17, v18, v15
	v_fma_f32 v14, -v14, v17, v16
	v_div_fmas_f32 v14, v14, v15, v17
	v_div_fixup_f32 v10, v14, v10, 1.0
	v_pk_mul_f32 v[10:11], v[10:11], s[36:37] op_sel_hi:[1,0]
	v_mul_f32_e32 v195, 0.5, v210
	v_cvt_pk_f16_f32 v9, v10, v11
	v_and_b32_e32 v10, 0xffff0000, v9
	v_lshlrev_b32_e32 v11, 16, v9
	v_or_b32_sdwa v9, v10, v8 dst_sel:DWORD dst_unused:UNUSED_PAD src0_sel:DWORD src1_sel:WORD_1
	v_or_b32_sdwa v8, v11, v8 dst_sel:DWORD dst_unused:UNUSED_PAD src0_sel:DWORD src1_sel:WORD_0
	v_pk_add_f32 v[10:11], v[12:13], 1.0 op_sel_hi:[1,0]
	v_mul_f32_e32 v196, 0.5, v211
	v_div_scale_f32 v12, s[6:7], v11, v11, 1.0
	v_rcp_f32_e32 v13, v12
	s_nop 0
	v_fma_f32 v14, -v12, v13, 1.0
	v_fmac_f32_e32 v13, v14, v13
	v_div_scale_f32 v14, vcc, 1.0, v11, 1.0
	v_mul_f32_e32 v15, v14, v13
	v_fma_f32 v16, -v12, v15, v14
	v_fmac_f32_e32 v15, v16, v13
	v_fma_f32 v12, -v12, v15, v14
	v_div_fmas_f32 v12, v12, v13, v15
	v_div_fixup_f32 v11, v12, v11, 1.0
	v_div_scale_f32 v12, s[6:7], v10, v10, 1.0
	v_rcp_f32_e32 v13, v12
	s_nop 0
	v_fma_f32 v14, -v12, v13, 1.0
	v_fmac_f32_e32 v13, v14, v13
	v_div_scale_f32 v14, vcc, 1.0, v10, 1.0
	v_mul_f32_e32 v15, v14, v13
	v_fma_f32 v16, -v12, v15, v14
	v_fmac_f32_e32 v15, v16, v13
	v_fma_f32 v12, -v12, v15, v14
	v_div_fmas_f32 v12, v12, v13, v15
	v_div_fixup_f32 v10, v12, v10, 1.0
	v_pk_add_f32 v[12:13], v[138:139], 1.0 op_sel_hi:[1,0]
	v_pk_mul_f32 v[10:11], v[10:11], s[36:37] op_sel_hi:[1,0]
	v_div_scale_f32 v14, s[6:7], v13, v13, 1.0
	v_rcp_f32_e32 v15, v14
	v_cvt_pk_f16_f32 v10, v10, v11
	v_fma_f32 v16, -v14, v15, 1.0
	v_fmac_f32_e32 v15, v16, v15
	v_div_scale_f32 v16, vcc, 1.0, v13, 1.0
	v_mul_f32_e32 v17, v16, v15
	v_fma_f32 v18, -v14, v17, v16
	v_fmac_f32_e32 v17, v18, v15
	v_fma_f32 v14, -v14, v17, v16
	v_div_fmas_f32 v14, v14, v15, v17
	v_div_fixup_f32 v13, v14, v13, 1.0
	v_div_scale_f32 v14, s[6:7], v12, v12, 1.0
	v_rcp_f32_e32 v15, v14
	s_nop 0
	v_fma_f32 v16, -v14, v15, 1.0
	v_fmac_f32_e32 v15, v16, v15
	v_div_scale_f32 v16, vcc, 1.0, v12, 1.0
	v_mul_f32_e32 v17, v16, v15
	v_fma_f32 v18, -v14, v17, v16
	v_fmac_f32_e32 v17, v18, v15
	v_fma_f32 v14, -v14, v17, v16
	v_div_fmas_f32 v14, v14, v15, v17
	v_div_fixup_f32 v12, v14, v12, 1.0
	v_pk_mul_f32 v[12:13], v[12:13], s[36:37] op_sel_hi:[1,0]
	s_nop 0
	v_cvt_pk_f16_f32 v11, v12, v13
	v_and_b32_e32 v12, 0xffff0000, v11
	v_lshlrev_b32_e32 v13, 16, v11
	v_or_b32_sdwa v11, v12, v10 dst_sel:DWORD dst_unused:UNUSED_PAD src0_sel:DWORD src1_sel:WORD_1
	v_or_b32_sdwa v10, v13, v10 dst_sel:DWORD dst_unused:UNUSED_PAD src0_sel:DWORD src1_sel:WORD_0
	v_pk_add_f32 v[12:13], v[22:23], 1.0 op_sel_hi:[1,0]
	s_nop 0
	v_div_scale_f32 v14, s[6:7], v13, v13, 1.0
	v_rcp_f32_e32 v15, v14
	s_nop 0
	v_fma_f32 v16, -v14, v15, 1.0
	v_fmac_f32_e32 v15, v16, v15
	v_div_scale_f32 v16, vcc, 1.0, v13, 1.0
	v_mul_f32_e32 v17, v16, v15
	v_fma_f32 v18, -v14, v17, v16
	v_fmac_f32_e32 v17, v18, v15
	v_fma_f32 v14, -v14, v17, v16
; #define UFOR(v, n) _Pragma("unroll") for (int v = 0; v < (n); ++v)
; __device__ __forceinline__ float sigmoidf_(float x) { return 1.f / (1.f + __expf(-x)); }
; __device__ __forceinline__ void phase_features(KP p, int l) {
;     ...
;         unpack8(*(const uint4*)(smem + F_KL + (tok * RW + ch) * 2), kv); unpack8(*(const uint4*)(smem + F_KK + (tok * RW + ch) * 2), kkn);
;         unpack8(*(const uint4*)(smem + F_RL + (tok * RW + ch) * 2), rr);
;         ld8f(w0 + ch, cw0); ld8f(w0 + RW + ch, cw1); ld8f(a0 + ch, ca0); ld8f(a0 + RW + ch, ca1); ld8f(ka_ + ch, cka); ld8f(rk_ + ch, crk);
;         float d0[8], d1[8], k0[8], k1[8], b0[8], b1[8];
;         float bon = 0.f;
;         UFOR(x, 8) {
;           d0[x] = 0.6065306597126334f * sigmoidf_(cw0[x] + xw0[x]);
;           d1[x] = 0.6065306597126334f * sigmoidf_(cw1[x] + xw1[x]);
;           const float av0 = sigmoidf_(ca0[x] + ya0[x]), av1 = sigmoidf_(ca1[x] + ya1[x]);
;           k0[x] = kv[x] * (1.f + (av0 - 1.f) * cka[x]); k1[x] = kv[x] * (1.f + (av1 - 1.f) * cka[x]);
;           b0[x] = kkn[x] * av0; b1[x] = kkn[x] * av1;
;           bon += rr[x] * 0.5f * (k0[x] + k1[x]) * crk[x];
;         }
	v_div_fmas_f32 v14, v14, v15, v17
	v_div_fixup_f32 v13, v14, v13, 1.0
	v_div_scale_f32 v14, s[6:7], v12, v12, 1.0
	v_rcp_f32_e32 v15, v14
	s_nop 0
	v_fma_f32 v16, -v14, v15, 1.0
	v_fmac_f32_e32 v15, v16, v15
	v_div_scale_f32 v16, vcc, 1.0, v12, 1.0
	v_mul_f32_e32 v17, v16, v15
	v_fma_f32 v18, -v14, v17, v16
	v_fmac_f32_e32 v17, v18, v15
	v_fma_f32 v14, -v14, v17, v16
	v_div_fmas_f32 v14, v14, v15, v17
	v_div_fixup_f32 v12, v14, v12, 1.0
	v_pk_add_f32 v[14:15], v[136:137], 1.0 op_sel_hi:[1,0]
	v_pk_mul_f32 v[12:13], v[12:13], s[36:37] op_sel_hi:[1,0]
	v_div_scale_f32 v16, s[6:7], v15, v15, 1.0
	v_rcp_f32_e32 v17, v16
	v_cvt_pk_f16_f32 v12, v12, v13
	v_pk_add_f32 v[136:137], v[142:143], 1.0 op_sel_hi:[1,0]
	v_fma_f32 v18, -v16, v17, 1.0
	v_fmac_f32_e32 v17, v18, v17
	v_div_scale_f32 v18, vcc, 1.0, v15, 1.0
	v_mul_f32_e32 v19, v18, v17
	v_fma_f32 v22, -v16, v19, v18
	v_fmac_f32_e32 v19, v22, v17
	v_fma_f32 v16, -v16, v19, v18
	v_div_fmas_f32 v16, v16, v17, v19
	v_div_fixup_f32 v15, v16, v15, 1.0
	v_div_scale_f32 v16, s[6:7], v14, v14, 1.0
	v_rcp_f32_e32 v17, v16
	v_div_scale_f32 v134, s[6:7], v137, v137, 1.0
	v_rcp_f32_e32 v138, v134
	v_fma_f32 v18, -v16, v17, 1.0
	v_fmac_f32_e32 v17, v18, v17
	v_div_scale_f32 v18, vcc, 1.0, v14, 1.0
	v_mul_f32_e32 v19, v18, v17
	v_fma_f32 v22, -v16, v19, v18
	v_fmac_f32_e32 v19, v22, v17
	v_fma_f32 v16, -v16, v19, v18
	v_div_fmas_f32 v16, v16, v17, v19
	v_div_fixup_f32 v14, v16, v14, 1.0
	v_pk_mul_f32 v[14:15], v[14:15], s[36:37] op_sel_hi:[1,0]
	v_fma_f32 v139, -v134, v138, 1.0
	v_cvt_pk_f16_f32 v13, v14, v15
	v_and_b32_e32 v14, 0xffff0000, v13
	v_lshlrev_b32_e32 v15, 16, v13
	v_or_b32_sdwa v13, v14, v12 dst_sel:DWORD dst_unused:UNUSED_PAD src0_sel:DWORD src1_sel:WORD_1
	v_or_b32_sdwa v12, v15, v12 dst_sel:DWORD dst_unused:UNUSED_PAD src0_sel:DWORD src1_sel:WORD_0
	v_pk_add_f32 v[14:15], v[20:21], 1.0 op_sel_hi:[1,0]
	v_fmac_f32_e32 v138, v139, v138
	v_div_scale_f32 v16, s[6:7], v15, v15, 1.0
	v_rcp_f32_e32 v17, v16
	s_nop 0
	v_fma_f32 v18, -v16, v17, 1.0
	v_fmac_f32_e32 v17, v18, v17
	v_div_scale_f32 v18, vcc, 1.0, v15, 1.0
	v_mul_f32_e32 v19, v18, v17
	v_fma_f32 v20, -v16, v19, v18
	v_fmac_f32_e32 v19, v20, v17
	v_fma_f32 v16, -v16, v19, v18
	v_div_fmas_f32 v16, v16, v17, v19
	v_div_fixup_f32 v15, v16, v15, 1.0
	v_div_scale_f32 v16, s[6:7], v14, v14, 1.0
	v_rcp_f32_e32 v17, v16
	s_nop 0
	v_fma_f32 v18, -v16, v17, 1.0
	v_fmac_f32_e32 v17, v18, v17
	v_div_scale_f32 v18, vcc, 1.0, v14, 1.0
	v_mul_f32_e32 v19, v18, v17
	v_fma_f32 v20, -v16, v19, v18
	v_fmac_f32_e32 v19, v20, v17
	v_fma_f32 v16, -v16, v19, v18
	v_div_fmas_f32 v16, v16, v17, v19
	v_div_fixup_f32 v14, v16, v14, 1.0
	v_pk_add_f32 v[16:17], v[140:141], 1.0 op_sel_hi:[1,0]
	v_pk_mul_f32 v[14:15], v[14:15], s[36:37] op_sel_hi:[1,0]
	v_div_scale_f32 v18, s[6:7], v17, v17, 1.0
	v_rcp_f32_e32 v19, v18
	v_cvt_pk_f16_f32 v14, v14, v15
	v_lshl_add_u64 v[140:141], s[58:59], 0, v[28:29]
	v_fma_f32 v20, -v18, v19, 1.0
	v_fmac_f32_e32 v19, v20, v19
	v_div_scale_f32 v20, vcc, 1.0, v17, 1.0
	v_mul_f32_e32 v21, v20, v19
	v_fma_f32 v22, -v18, v21, v20
	v_fmac_f32_e32 v21, v22, v19
	v_fma_f32 v18, -v18, v21, v20
	v_div_fmas_f32 v18, v18, v19, v21
	v_div_fixup_f32 v17, v18, v17, 1.0
	v_div_scale_f32 v18, s[6:7], v16, v16, 1.0
	v_rcp_f32_e32 v19, v18
	s_nop 0
	v_fma_f32 v20, -v18, v19, 1.0
	v_fmac_f32_e32 v19, v20, v19
	v_div_scale_f32 v20, vcc, 1.0, v16, 1.0
	v_mul_f32_e32 v21, v20, v19
	v_fma_f32 v22, -v18, v21, v20
	v_fmac_f32_e32 v21, v22, v19
	v_fma_f32 v18, -v18, v21, v20
	v_div_fmas_f32 v18, v18, v19, v21
	v_div_fixup_f32 v16, v18, v16, 1.0
	v_pk_mul_f32 v[16:17], v[16:17], s[36:37] op_sel_hi:[1,0]
	v_div_scale_f32 v139, vcc, 1.0, v137, 1.0
	v_cvt_pk_f16_f32 v15, v16, v17
	v_and_b32_e32 v16, 0xffff0000, v15
	v_lshlrev_b32_e32 v17, 16, v15
	v_or_b32_sdwa v15, v16, v14 dst_sel:DWORD dst_unused:UNUSED_PAD src0_sel:DWORD src1_sel:WORD_1
	v_or_b32_sdwa v14, v17, v14 dst_sel:DWORD dst_unused:UNUSED_PAD src0_sel:DWORD src1_sel:WORD_0
	ds_read_b128 v[16:19], v192 offset:8448
	global_load_dwordx4 v[20:23], v[24:25], off offset:16
	s_nop 0
	global_load_dwordx4 v[24:27], v[24:25], off
	v_mul_f32_e32 v142, v139, v138
	v_fma_f32 v143, -v134, v142, v139
	v_fmac_f32_e32 v142, v143, v138
	v_fma_f32 v134, -v134, v142, v139
	v_div_fmas_f32 v134, v134, v138, v142
	v_div_fixup_f32 v143, v134, v137, 1.0
	v_div_scale_f32 v134, s[6:7], v136, v136, 1.0
	v_rcp_f32_e32 v137, v134
	s_waitcnt lgkmcnt(0)
	v_lshlrev_b32_e32 v145, 16, v17
	v_lshlrev_b32_e32 v144, 16, v16
	v_and_b32_e32 v17, 0xffff0000, v17
	v_fma_f32 v138, -v134, v137, 1.0
	v_fmac_f32_e32 v137, v138, v137
	v_div_scale_f32 v138, vcc, 1.0, v136, 1.0
	v_mul_f32_e32 v139, v138, v137
	v_fma_f32 v142, -v134, v139, v138
	v_fmac_f32_e32 v139, v142, v137
	v_fma_f32 v134, -v134, v139, v138
	v_div_fmas_f32 v134, v134, v137, v139
	v_div_fixup_f32 v142, v134, v136, 1.0
	v_pk_add_f32 v[136:137], v[142:143], -1.0 op_sel_hi:[1,0]
	v_and_b32_e32 v16, 0xffff0000, v16
	v_lshlrev_b32_e32 v147, 16, v19
	v_lshlrev_b32_e32 v146, 16, v18
	s_waitcnt vmcnt(1)
	v_mov_b32_e32 v148, v20
	s_waitcnt vmcnt(0)
; #define UFOR(v, n) _Pragma("unroll") for (int v = 0; v < (n); ++v)
; __device__ __forceinline__ float sigmoidf_(float x) { return 1.f / (1.f + __expf(-x)); }
; __device__ __forceinline__ void phase_features(KP p, int l) {
;     ...
;         UFOR(x, 8) {
;           d0[x] = 0.6065306597126334f * sigmoidf_(cw0[x] + xw0[x]);
;           d1[x] = 0.6065306597126334f * sigmoidf_(cw1[x] + xw1[x]);
;           const float av0 = sigmoidf_(ca0[x] + ya0[x]), av1 = sigmoidf_(ca1[x] + ya1[x]);
;           k0[x] = kv[x] * (1.f + (av0 - 1.f) * cka[x]); k1[x] = kv[x] * (1.f + (av1 - 1.f) * cka[x]);
;           b0[x] = kkn[x] * av0; b1[x] = kkn[x] * av1;
;           bon += rr[x] * 0.5f * (k0[x] + k1[x]) * crk[x];
;         }
;         const size_t go = (size_t)r * RW + ch;
;         *(uint4*)(FA(3) + go) = packh8(d0); *(uint4*)(FA(4) + go) = packh8(d1);
;         *(uint4*)(FA(5) + go) = pack8(k0); *(uint4*)(FA(6) + go) = pack8(k1);
;         *(uint4*)(FA(7) + go) = pack8(b0); *(uint4*)(FA(8) + go) = pack8(b1);
	v_mov_b32_e32 v152, v24
	v_div_scale_f32 v24, s[6:7], v131, v131, 1.0
	v_mov_b32_e32 v153, v26
	v_rcp_f32_e32 v26, v24
	v_pk_fma_f32 v[150:151], v[136:137], v[152:153], 1.0 op_sel_hi:[1,1,0]
	v_div_scale_f32 v20, s[6:7], v125, v125, 1.0
	v_fma_f32 v134, -v24, v26, 1.0
	v_fmac_f32_e32 v26, v134, v26
	v_div_scale_f32 v134, vcc, 1.0, v131, 1.0
	v_mul_f32_e32 v138, v134, v26
	v_fma_f32 v139, -v24, v138, v134
	v_fmac_f32_e32 v138, v139, v26
	v_fma_f32 v24, -v24, v138, v134
	v_div_fmas_f32 v24, v24, v26, v138
	v_div_fixup_f32 v131, v24, v131, 1.0
	v_div_scale_f32 v24, s[6:7], v130, v130, 1.0
	v_rcp_f32_e32 v26, v24
	v_pk_mul_f32 v[136:137], v[150:151], v[144:145]
	v_mov_b32_e32 v149, v22
	v_rcp_f32_e32 v22, v20
	v_fma_f32 v134, -v24, v26, 1.0
	v_fmac_f32_e32 v26, v134, v26
	v_div_scale_f32 v134, vcc, 1.0, v130, 1.0
	v_mul_f32_e32 v138, v134, v26
	v_fma_f32 v139, -v24, v138, v134
	v_fmac_f32_e32 v138, v139, v26
	v_fma_f32 v24, -v24, v138, v134
	v_div_fmas_f32 v24, v24, v26, v138
	v_div_fixup_f32 v130, v24, v130, 1.0
	v_pk_add_f32 v[138:139], v[130:131], -1.0 op_sel_hi:[1,0]
	v_mov_b32_e32 v26, v25
	v_pk_fma_f32 v[154:155], v[138:139], v[26:27], 1.0 op_sel_hi:[1,1,0]
	v_and_b32_sdwa v134, v137, v207 dst_sel:DWORD dst_unused:UNUSED_PAD src0_sel:WORD_1 src1_sel:DWORD
	v_pk_mul_f32 v[24:25], v[154:155], v[16:17]
	v_and_b32_sdwa v138, v136, v207 dst_sel:DWORD dst_unused:UNUSED_PAD src0_sel:WORD_1 src1_sel:DWORD
	v_add3_u32 v136, v136, v138, s31
	v_add3_u32 v134, v137, v134, s31
	v_and_b32_sdwa v137, v25, v207 dst_sel:DWORD dst_unused:UNUSED_PAD src0_sel:WORD_1 src1_sel:DWORD
	v_and_b32_sdwa v138, v24, v207 dst_sel:DWORD dst_unused:UNUSED_PAD src0_sel:WORD_1 src1_sel:DWORD
	v_add3_u32 v25, v25, v137, s31
	v_add3_u32 v24, v24, v138, s31
	v_and_b32_e32 v25, 0xffff0000, v25
	v_and_b32_e32 v24, 0xffff0000, v24
	v_or_b32_sdwa v203, v25, v134 dst_sel:DWORD dst_unused:UNUSED_PAD src0_sel:DWORD src1_sel:WORD_1
	v_or_b32_sdwa v202, v24, v136 dst_sel:DWORD dst_unused:UNUSED_PAD src0_sel:DWORD src1_sel:WORD_1
	v_and_b32_e32 v25, 0xffff0000, v19
	v_and_b32_e32 v24, 0xffff0000, v18
	v_pk_add_f32 v[18:19], v[128:129], 1.0 op_sel_hi:[1,0]
	s_nop 0
	v_div_scale_f32 v128, s[6:7], v19, v19, 1.0
	v_rcp_f32_e32 v129, v128
	s_nop 0
	v_fma_f32 v134, -v128, v129, 1.0
	v_fmac_f32_e32 v129, v134, v129
	v_div_scale_f32 v134, vcc, 1.0, v19, 1.0
	v_mul_f32_e32 v136, v134, v129
	v_fma_f32 v137, -v128, v136, v134
	v_fmac_f32_e32 v136, v137, v129
	v_fma_f32 v128, -v128, v136, v134
	v_div_fmas_f32 v128, v128, v129, v136
	v_div_fixup_f32 v19, v128, v19, 1.0
	v_div_scale_f32 v128, s[6:7], v18, v18, 1.0
	v_rcp_f32_e32 v129, v128
	s_nop 0
	v_fma_f32 v134, -v128, v129, 1.0
	v_fmac_f32_e32 v129, v134, v129
	v_div_scale_f32 v134, vcc, 1.0, v18, 1.0
	v_mul_f32_e32 v136, v134, v129
	v_fma_f32 v137, -v128, v136, v134
	v_fmac_f32_e32 v136, v137, v129
	v_fma_f32 v128, -v128, v136, v134
	v_fma_f32 v134, -v20, v22, 1.0
	v_div_fmas_f32 v128, v128, v129, v136
	v_fmac_f32_e32 v22, v134, v22
	v_div_scale_f32 v134, vcc, 1.0, v125, 1.0
	v_mul_f32_e32 v138, v134, v22
	v_fma_f32 v139, -v20, v138, v134
	v_fmac_f32_e32 v138, v139, v22
	v_fma_f32 v20, -v20, v138, v134
	v_div_fmas_f32 v20, v20, v22, v138
	v_div_fixup_f32 v125, v20, v125, 1.0
	v_div_scale_f32 v20, s[6:7], v124, v124, 1.0
	v_rcp_f32_e32 v22, v20
	v_div_fixup_f32 v18, v128, v18, 1.0
	v_pk_add_f32 v[128:129], v[18:19], -1.0 op_sel_hi:[1,0]
	v_fma_f32 v134, -v20, v22, 1.0
	v_fmac_f32_e32 v22, v134, v22
	v_div_scale_f32 v134, vcc, 1.0, v124, 1.0
	v_mul_f32_e32 v138, v134, v22
	v_fma_f32 v139, -v20, v138, v134
	v_fmac_f32_e32 v138, v139, v22
	v_fma_f32 v20, -v20, v138, v134
	v_div_fmas_f32 v20, v20, v22, v138
	v_div_fixup_f32 v124, v20, v124, 1.0
	v_pk_fma_f32 v[128:129], v[128:129], v[148:149], 1.0 op_sel_hi:[1,1,0]
	v_pk_add_f32 v[138:139], v[124:125], -1.0 op_sel_hi:[1,0]
	v_mov_b32_e32 v22, v21
	v_pk_mul_f32 v[136:137], v[128:129], v[146:147]
	v_pk_fma_f32 v[20:21], v[138:139], v[22:23], 1.0 op_sel_hi:[1,1,0]
	v_and_b32_sdwa v134, v137, v207 dst_sel:DWORD dst_unused:UNUSED_PAD src0_sel:WORD_1 src1_sel:DWORD
	v_pk_mul_f32 v[138:139], v[20:21], v[24:25]
	v_and_b32_sdwa v201, v136, v207 dst_sel:DWORD dst_unused:UNUSED_PAD src0_sel:WORD_1 src1_sel:DWORD
	v_add3_u32 v136, v136, v201, s31
	v_add3_u32 v134, v137, v134, s31
	v_and_b32_sdwa v137, v139, v207 dst_sel:DWORD dst_unused:UNUSED_PAD src0_sel:WORD_1 src1_sel:DWORD
	v_and_b32_sdwa v201, v138, v207 dst_sel:DWORD dst_unused:UNUSED_PAD src0_sel:WORD_1 src1_sel:DWORD
	v_add3_u32 v137, v139, v137, s31
	v_add3_u32 v138, v138, v201, s31
	v_and_b32_e32 v137, 0xffff0000, v137
	v_and_b32_e32 v138, 0xffff0000, v138
	v_or_b32_sdwa v205, v137, v134 dst_sel:DWORD dst_unused:UNUSED_PAD src0_sel:DWORD src1_sel:WORD_1
	v_or_b32_sdwa v204, v138, v136 dst_sel:DWORD dst_unused:UNUSED_PAD src0_sel:DWORD src1_sel:WORD_1
	global_store_dwordx4 v[122:123], v[8:11], off
	global_store_dwordx4 v[126:127], v[12:15], off
	global_store_dwordx4 v[140:141], v[202:205], off
	v_pk_add_f32 v[8:9], v[120:121], 1.0 op_sel_hi:[1,0]
	v_lshl_add_u64 v[10:11], s[62:63], 0, v[28:29]
	v_div_scale_f32 v12, s[6:7], v9, v9, 1.0
	v_rcp_f32_e32 v13, v12
	s_nop 0
	v_fma_f32 v14, -v12, v13, 1.0
	v_fmac_f32_e32 v13, v14, v13
	v_div_scale_f32 v14, vcc, 1.0, v9, 1.0
	v_mul_f32_e32 v15, v14, v13
	v_fma_f32 v120, -v12, v15, v14
	v_fmac_f32_e32 v15, v120, v13
	v_fma_f32 v12, -v12, v15, v14
	v_div_fmas_f32 v12, v12, v13, v15
	v_div_fixup_f32 v9, v12, v9, 1.0
	v_div_scale_f32 v12, s[6:7], v8, v8, 1.0
	v_rcp_f32_e32 v13, v12
	s_nop 0
	v_fma_f32 v14, -v12, v13, 1.0
	v_fmac_f32_e32 v13, v14, v13
	v_div_scale_f32 v14, vcc, 1.0, v8, 1.0
	v_mul_f32_e32 v15, v14, v13
; #define UFOR(v, n) _Pragma("unroll") for (int v = 0; v < (n); ++v)
; __device__ __forceinline__ float sigmoidf_(float x) { return 1.f / (1.f + __expf(-x)); }
; __device__ __forceinline__ void phase_features(KP p, int l) {
;     ...
;         UFOR(x, 8) {
;           d0[x] = 0.6065306597126334f * sigmoidf_(cw0[x] + xw0[x]);
;           d1[x] = 0.6065306597126334f * sigmoidf_(cw1[x] + xw1[x]);
;           const float av0 = sigmoidf_(ca0[x] + ya0[x]), av1 = sigmoidf_(ca1[x] + ya1[x]);
;           k0[x] = kv[x] * (1.f + (av0 - 1.f) * cka[x]); k1[x] = kv[x] * (1.f + (av1 - 1.f) * cka[x]);
;           b0[x] = kkn[x] * av0; b1[x] = kkn[x] * av1;
;           bon += rr[x] * 0.5f * (k0[x] + k1[x]) * crk[x];
;         }
;         const size_t go = (size_t)r * RW + ch;
;         *(uint4*)(FA(3) + go) = packh8(d0); *(uint4*)(FA(4) + go) = packh8(d1);
;         *(uint4*)(FA(5) + go) = pack8(k0); *(uint4*)(FA(6) + go) = pack8(k1);
;         *(uint4*)(FA(7) + go) = pack8(b0); *(uint4*)(FA(8) + go) = pack8(b1);
	v_fma_f32 v120, -v12, v15, v14
	v_fmac_f32_e32 v15, v120, v13
	v_fma_f32 v12, -v12, v15, v14
	v_div_fmas_f32 v12, v12, v13, v15
	v_div_fixup_f32 v8, v12, v8, 1.0
	v_pk_add_f32 v[12:13], v[34:35], 1.0 op_sel_hi:[1,0]
	s_nop 0
	v_div_scale_f32 v14, s[6:7], v13, v13, 1.0
	v_rcp_f32_e32 v15, v14
	s_nop 0
	v_fma_f32 v34, -v14, v15, 1.0
	v_fmac_f32_e32 v15, v34, v15
	v_div_scale_f32 v34, vcc, 1.0, v13, 1.0
	v_mul_f32_e32 v35, v34, v15
	v_fma_f32 v120, -v14, v35, v34
	v_fmac_f32_e32 v35, v120, v15
	v_fma_f32 v14, -v14, v35, v34
	v_div_fmas_f32 v14, v14, v15, v35
	v_div_fixup_f32 v13, v14, v13, 1.0
	v_div_scale_f32 v14, s[6:7], v12, v12, 1.0
	v_rcp_f32_e32 v15, v14
	s_nop 0
	v_fma_f32 v34, -v14, v15, 1.0
	v_fmac_f32_e32 v15, v34, v15
	v_div_scale_f32 v34, vcc, 1.0, v12, 1.0
	v_mul_f32_e32 v35, v34, v15
	v_fma_f32 v120, -v14, v35, v34
	v_fmac_f32_e32 v35, v120, v15
	v_fma_f32 v14, -v14, v35, v34
	v_div_fmas_f32 v14, v14, v15, v35
	v_div_fixup_f32 v12, v14, v12, 1.0
	v_pk_add_f32 v[14:15], v[8:9], -1.0 op_sel_hi:[1,0]
	v_pk_add_f32 v[34:35], v[12:13], -1.0 op_sel_hi:[1,0]
	v_pk_fma_f32 v[14:15], v[14:15], v[152:153], 1.0 op_sel_hi:[1,1,0]
	v_pk_fma_f32 v[26:27], v[34:35], v[26:27], 1.0 op_sel_hi:[1,1,0]
	v_pk_mul_f32 v[14:15], v[14:15], v[144:145]
	v_pk_mul_f32 v[26:27], v[26:27], v[16:17]
	v_pk_fma_f32 v[120:121], v[150:151], v[144:145], v[14:15]
	v_pk_fma_f32 v[16:17], v[154:155], v[16:17], v[26:27]
	v_mul_f32_e32 v120, v197, v120
	v_fma_f32 v4, v120, v4, 0
	v_mul_f32_e32 v16, v198, v16
	v_fmac_f32_e32 v4, v16, v5
	v_mul_f32_e32 v5, v199, v121
	v_fmac_f32_e32 v4, v5, v6
	v_mul_f32_e32 v5, v200, v17
	v_and_b32_sdwa v6, v14, v207 dst_sel:DWORD dst_unused:UNUSED_PAD src0_sel:WORD_1 src1_sel:DWORD
	v_fmac_f32_e32 v4, v5, v7
	v_add3_u32 v6, v14, v6, s31
	v_and_b32_sdwa v7, v27, v207 dst_sel:DWORD dst_unused:UNUSED_PAD src0_sel:WORD_1 src1_sel:DWORD
	v_and_b32_sdwa v14, v26, v207 dst_sel:DWORD dst_unused:UNUSED_PAD src0_sel:WORD_1 src1_sel:DWORD
	v_and_b32_sdwa v5, v15, v207 dst_sel:DWORD dst_unused:UNUSED_PAD src0_sel:WORD_1 src1_sel:DWORD
	v_add3_u32 v7, v27, v7, s31
	v_add3_u32 v14, v26, v14, s31
	v_add3_u32 v5, v15, v5, s31
	v_and_b32_e32 v7, 0xffff0000, v7
	v_and_b32_e32 v14, 0xffff0000, v14
	v_or_b32_sdwa v15, v7, v5 dst_sel:DWORD dst_unused:UNUSED_PAD src0_sel:DWORD src1_sel:WORD_1
	v_or_b32_sdwa v14, v14, v6 dst_sel:DWORD dst_unused:UNUSED_PAD src0_sel:DWORD src1_sel:WORD_1
	v_pk_add_f32 v[6:7], v[32:33], 1.0 op_sel_hi:[1,0]
	s_nop 0
	v_div_scale_f32 v5, s[6:7], v7, v7, 1.0
	v_rcp_f32_e32 v16, v5
	s_nop 0
	v_fma_f32 v17, -v5, v16, 1.0
	v_fmac_f32_e32 v16, v17, v16
	v_div_scale_f32 v17, vcc, 1.0, v7, 1.0
	v_mul_f32_e32 v26, v17, v16
	v_fma_f32 v27, -v5, v26, v17
	v_fmac_f32_e32 v26, v27, v16
	v_fma_f32 v5, -v5, v26, v17
	v_div_fmas_f32 v5, v5, v16, v26
	v_div_fixup_f32 v7, v5, v7, 1.0
	v_div_scale_f32 v5, s[6:7], v6, v6, 1.0
	v_rcp_f32_e32 v16, v5
	s_nop 0
	v_fma_f32 v17, -v5, v16, 1.0
	v_fmac_f32_e32 v16, v17, v16
	v_div_scale_f32 v17, vcc, 1.0, v6, 1.0
	v_mul_f32_e32 v26, v17, v16
	v_fma_f32 v27, -v5, v26, v17
	v_fmac_f32_e32 v26, v27, v16
	v_fma_f32 v5, -v5, v26, v17
	v_div_fmas_f32 v5, v5, v16, v26
	v_pk_add_f32 v[16:17], v[30:31], 1.0 op_sel_hi:[1,0]
	v_div_fixup_f32 v6, v5, v6, 1.0
	v_div_scale_f32 v5, s[6:7], v17, v17, 1.0
	v_rcp_f32_e32 v26, v5
	s_nop 0
	v_fma_f32 v27, -v5, v26, 1.0
	v_fmac_f32_e32 v26, v27, v26
	v_div_scale_f32 v27, vcc, 1.0, v17, 1.0
	v_mul_f32_e32 v30, v27, v26
	v_fma_f32 v31, -v5, v30, v27
	v_fmac_f32_e32 v30, v31, v26
	v_fma_f32 v5, -v5, v30, v27
	v_div_fmas_f32 v5, v5, v26, v30
	v_div_fixup_f32 v27, v5, v17, 1.0
	v_div_scale_f32 v5, s[6:7], v16, v16, 1.0
	v_rcp_f32_e32 v17, v5
	s_nop 0
	v_fma_f32 v26, -v5, v17, 1.0
	v_fmac_f32_e32 v17, v26, v17
	v_div_scale_f32 v26, vcc, 1.0, v16, 1.0
	v_mul_f32_e32 v30, v26, v17
	v_fma_f32 v31, -v5, v30, v26
	v_fmac_f32_e32 v30, v31, v17
	v_fma_f32 v5, -v5, v30, v26
	v_div_fmas_f32 v5, v5, v17, v30
	v_div_fixup_f32 v26, v5, v16, 1.0
	v_pk_add_f32 v[16:17], v[6:7], -1.0 op_sel_hi:[1,0]
	v_pk_add_f32 v[30:31], v[26:27], -1.0 op_sel_hi:[1,0]
	v_pk_fma_f32 v[16:17], v[16:17], v[148:149], 1.0 op_sel_hi:[1,1,0]
	v_pk_fma_f32 v[22:23], v[30:31], v[22:23], 1.0 op_sel_hi:[1,1,0]
	v_pk_mul_f32 v[16:17], v[16:17], v[146:147]
	v_pk_mul_f32 v[22:23], v[22:23], v[24:25]
	v_pk_fma_f32 v[32:33], v[128:129], v[146:147], v[16:17]
	v_pk_fma_f32 v[20:21], v[20:21], v[24:25], v[22:23]
	v_mul_f32_e32 v5, v193, v32
	v_mul_f32_e32 v20, v194, v20
	v_fmac_f32_e32 v4, v5, v0
	v_mul_f32_e32 v24, v195, v33
	v_fmac_f32_e32 v4, v20, v1
	v_mul_f32_e32 v21, v196, v21
	v_fmac_f32_e32 v4, v24, v2
	v_and_b32_sdwa v25, v17, v207 dst_sel:DWORD dst_unused:UNUSED_PAD src0_sel:WORD_1 src1_sel:DWORD
	v_and_b32_sdwa v30, v16, v207 dst_sel:DWORD dst_unused:UNUSED_PAD src0_sel:WORD_1 src1_sel:DWORD
	v_fmac_f32_e32 v4, v21, v3
	ds_read_b128 v[0:3], v192 offset:33024
	v_add3_u32 v16, v16, v30, s31
	v_add3_u32 v17, v17, v25, s31
	v_and_b32_sdwa v25, v23, v207 dst_sel:DWORD dst_unused:UNUSED_PAD src0_sel:WORD_1 src1_sel:DWORD
	v_and_b32_sdwa v30, v22, v207 dst_sel:DWORD dst_unused:UNUSED_PAD src0_sel:WORD_1 src1_sel:DWORD
	v_add3_u32 v23, v23, v25, s31
	v_add3_u32 v22, v22, v30, s31
	v_and_b32_e32 v23, 0xffff0000, v23
	v_and_b32_e32 v22, 0xffff0000, v22
	v_or_b32_sdwa v17, v23, v17 dst_sel:DWORD dst_unused:UNUSED_PAD src0_sel:DWORD src1_sel:WORD_1
	v_or_b32_sdwa v16, v22, v16 dst_sel:DWORD dst_unused:UNUSED_PAD src0_sel:DWORD src1_sel:WORD_1
	global_store_dwordx4 v[10:11], v[14:17], off
	s_waitcnt lgkmcnt(0)
; __device__ __forceinline__ void phase_features(KP p, int l) {
;     ...
;           b0[x] = kkn[x] * av0; b1[x] = kkn[x] * av1;
;           bon += rr[x] * 0.5f * (k0[x] + k1[x]) * crk[x];
;         }
;         const size_t go = (size_t)r * RW + ch;
;         *(uint4*)(FA(3) + go) = packh8(d0); *(uint4*)(FA(4) + go) = packh8(d1);
;         *(uint4*)(FA(5) + go) = pack8(k0); *(uint4*)(FA(6) + go) = pack8(k1);
;         *(uint4*)(FA(7) + go) = pack8(b0); *(uint4*)(FA(8) + go) = pack8(b1);
;         *(uint4*)(FA(9) + go) = pack8(gg);
;         bon += dppf<0xB1>(bon); bon += dppf<0x4E>(bon);
;         if (g4 == 0) atomicAdd(&sbl[tok * 12 + hd], bon);
	v_and_b32_e32 v23, 0xffff0000, v3
	v_lshl_add_u64 v[10:11], s[66:67], 0, v[28:29]
	v_lshlrev_b32_e32 v15, 16, v1
	v_lshlrev_b32_e32 v14, 16, v0
	v_and_b32_e32 v17, 0xffff0000, v1
	v_and_b32_e32 v16, 0xffff0000, v0
	v_pk_mul_f32 v[0:1], v[142:143], v[14:15]
	v_pk_mul_f32 v[20:21], v[130:131], v[16:17]
	v_and_b32_sdwa v22, v0, v207 dst_sel:DWORD dst_unused:UNUSED_PAD src0_sel:WORD_1 src1_sel:DWORD
	v_add3_u32 v0, v0, v22, s31
	v_and_b32_sdwa v22, v20, v207 dst_sel:DWORD dst_unused:UNUSED_PAD src0_sel:WORD_1 src1_sel:DWORD
	v_and_b32_sdwa v5, v1, v207 dst_sel:DWORD dst_unused:UNUSED_PAD src0_sel:WORD_1 src1_sel:DWORD
	v_add3_u32 v20, v20, v22, s31
	v_add3_u32 v1, v1, v5, s31
	v_and_b32_sdwa v5, v21, v207 dst_sel:DWORD dst_unused:UNUSED_PAD src0_sel:WORD_1 src1_sel:DWORD
	v_and_b32_e32 v20, 0xffff0000, v20
	v_add3_u32 v5, v21, v5, s31
	v_or_b32_sdwa v0, v20, v0 dst_sel:DWORD dst_unused:UNUSED_PAD src0_sel:DWORD src1_sel:WORD_1
	v_lshlrev_b32_e32 v21, 16, v3
	v_lshlrev_b32_e32 v20, 16, v2
	v_and_b32_e32 v5, 0xffff0000, v5
	v_and_b32_e32 v22, 0xffff0000, v2
	v_pk_mul_f32 v[2:3], v[18:19], v[20:21]
	v_or_b32_sdwa v1, v5, v1 dst_sel:DWORD dst_unused:UNUSED_PAD src0_sel:DWORD src1_sel:WORD_1
	v_pk_mul_f32 v[18:19], v[124:125], v[22:23]
	v_and_b32_sdwa v5, v3, v207 dst_sel:DWORD dst_unused:UNUSED_PAD src0_sel:WORD_1 src1_sel:DWORD
	v_and_b32_sdwa v24, v2, v207 dst_sel:DWORD dst_unused:UNUSED_PAD src0_sel:WORD_1 src1_sel:DWORD
	v_add3_u32 v2, v2, v24, s31
	v_add3_u32 v3, v3, v5, s31
	v_and_b32_sdwa v5, v19, v207 dst_sel:DWORD dst_unused:UNUSED_PAD src0_sel:WORD_1 src1_sel:DWORD
	v_and_b32_sdwa v24, v18, v207 dst_sel:DWORD dst_unused:UNUSED_PAD src0_sel:WORD_1 src1_sel:DWORD
	v_add3_u32 v5, v19, v5, s31
	v_add3_u32 v18, v18, v24, s31
	v_and_b32_e32 v5, 0xffff0000, v5
	v_and_b32_e32 v18, 0xffff0000, v18
	v_or_b32_sdwa v3, v5, v3 dst_sel:DWORD dst_unused:UNUSED_PAD src0_sel:DWORD src1_sel:WORD_1
	v_or_b32_sdwa v2, v18, v2 dst_sel:DWORD dst_unused:UNUSED_PAD src0_sel:DWORD src1_sel:WORD_1
	global_store_dwordx4 v[10:11], v[0:3], off
	v_lshl_add_u64 v[10:11], s[70:71], 0, v[28:29]
	s_nop 0
	v_pk_mul_f32 v[0:1], v[8:9], v[14:15]
	v_pk_mul_f32 v[2:3], v[12:13], v[16:17]
	v_and_b32_sdwa v5, v1, v207 dst_sel:DWORD dst_unused:UNUSED_PAD src0_sel:WORD_1 src1_sel:DWORD
	v_and_b32_sdwa v8, v0, v207 dst_sel:DWORD dst_unused:UNUSED_PAD src0_sel:WORD_1 src1_sel:DWORD
	v_add3_u32 v0, v0, v8, s31
	v_add3_u32 v1, v1, v5, s31
	v_and_b32_sdwa v5, v3, v207 dst_sel:DWORD dst_unused:UNUSED_PAD src0_sel:WORD_1 src1_sel:DWORD
	v_and_b32_sdwa v8, v2, v207 dst_sel:DWORD dst_unused:UNUSED_PAD src0_sel:WORD_1 src1_sel:DWORD
	v_add3_u32 v3, v3, v5, s31
	v_add3_u32 v2, v2, v8, s31
	v_and_b32_e32 v3, 0xffff0000, v3
	v_and_b32_e32 v2, 0xffff0000, v2
	v_or_b32_sdwa v1, v3, v1 dst_sel:DWORD dst_unused:UNUSED_PAD src0_sel:DWORD src1_sel:WORD_1
	v_or_b32_sdwa v0, v2, v0 dst_sel:DWORD dst_unused:UNUSED_PAD src0_sel:DWORD src1_sel:WORD_1
	v_pk_mul_f32 v[2:3], v[6:7], v[20:21]
	v_pk_mul_f32 v[6:7], v[26:27], v[22:23]
	v_and_b32_sdwa v8, v2, v207 dst_sel:DWORD dst_unused:UNUSED_PAD src0_sel:WORD_1 src1_sel:DWORD
	v_add3_u32 v2, v2, v8, s31
	v_and_b32_sdwa v8, v6, v207 dst_sel:DWORD dst_unused:UNUSED_PAD src0_sel:WORD_1 src1_sel:DWORD
	v_and_b32_sdwa v5, v3, v207 dst_sel:DWORD dst_unused:UNUSED_PAD src0_sel:WORD_1 src1_sel:DWORD
	v_add3_u32 v6, v6, v8, s31
	v_add3_u32 v3, v3, v5, s31
	v_and_b32_sdwa v5, v7, v207 dst_sel:DWORD dst_unused:UNUSED_PAD src0_sel:WORD_1 src1_sel:DWORD
	v_and_b32_e32 v6, 0xffff0000, v6
	v_add3_u32 v5, v7, v5, s31
	v_or_b32_sdwa v2, v6, v2 dst_sel:DWORD dst_unused:UNUSED_PAD src0_sel:DWORD src1_sel:WORD_1
	ds_read_b128 v[6:9], v188 offset:6144
	v_and_b32_e32 v5, 0xffff0000, v5
	v_or_b32_sdwa v3, v5, v3 dst_sel:DWORD dst_unused:UNUSED_PAD src0_sel:DWORD src1_sel:WORD_1
	global_store_dwordx4 v[10:11], v[0:3], off
	s_nop 1
	v_lshl_add_u64 v[0:1], s[74:75], 0, v[28:29]
	s_waitcnt lgkmcnt(0)
	global_store_dwordx4 v[0:1], v[6:9], off
	v_add_f32_dpp v0, v4, v4 quad_perm:[1,0,3,2] row_mask:0xf bank_mask:0xf bound_ctrl:1
	s_nop 1
	v_mov_b32_dpp v1, v0 quad_perm:[2,3,0,1] row_mask:0xf bank_mask:0xf bound_ctrl:1
	s_and_saveexec_b64 s[52:53], s[44:45]
	s_cbranch_execz .LBB0_686
	v_lshl_add_u32 v2, v191, 2, v164
	v_add_f32_e32 v0, v0, v1
	ds_add_f32 v2, v0
	s_branch .LBB0_686
